# out-proj prompt epilogue first half: vmcnt(0) replaced by counted waits 12/8/4/0 at each row group's first consumer
# baseline (speedup 1.0000x reference)
.LBB0_668:
	s_and_b64 vcc, exec, s[6:7]
	s_cbranch_vccz .LBB0_686
	s_ashr_i32 s3, s90, 3
	s_mul_hi_i32 s7, s3, 0x3000
	s_mulk_i32 s3, 0x3000
	v_readlane_b32 s36, v254, 50
	v_readlane_b32 s37, v254, 51
	s_add_u32 s6, s36, s3
	s_addc_u32 s7, s37, s7
	v_lshlrev_b64 v[132:133], 2, v[2:3]
	v_readlane_b32 s68, v254, 16
	s_waitcnt lgkmcnt(0)
	v_lshl_add_u64 v[134:135], s[6:7], 0, v[132:133]
	v_readlane_b32 s69, v254, 17
	v_lshl_add_u64 v[148:149], v[134:135], 0, s[54:55]
	v_add_co_u32_e32 v134, vcc, 0x2000, v134
	v_lshl_add_u64 v[212:213], s[68:69], 0, v[132:133]
	v_lshlrev_b64 v[132:133], 12, v[210:211]
	v_addc_co_u32_e32 v135, vcc, 0, v135, vcc
	v_lshl_add_u64 v[132:133], v[212:213], 0, v[132:133]
	global_load_dwordx4 v[232:235], v[132:133], off offset:16 nt
	global_load_dwordx4 v[140:143], v[148:149], off offset:16
	global_load_dwordx4 v[136:139], v[148:149], off offset:512
	global_load_dwordx4 v[236:239], v[132:133], off offset:512 nt
	global_load_dwordx4 v[144:147], v[134:135], off
	global_load_dwordx4 v[240:243], v[132:133], off nt
	global_load_dwordx4 v[244:247], v[132:133], off offset:528 nt
	s_nop 0
	global_load_dwordx4 v[132:135], v[148:149], off offset:528
	v_or_b32_e32 v218, 16, v210
	v_or_b32_e32 v216, 32, v210
	v_or_b32_e32 v214, 48, v210
	v_ashrrev_i32_e32 v219, 31, v218
	v_ashrrev_i32_e32 v217, 31, v216
	v_ashrrev_i32_e32 v215, 31, v214
	v_lshlrev_b64 v[148:149], 12, v[218:219]
	v_lshlrev_b64 v[150:151], 12, v[216:217]
	v_lshlrev_b64 v[152:153], 12, v[214:215]
	v_lshl_add_u64 v[148:149], v[212:213], 0, v[148:149]
	v_lshl_add_u64 v[150:151], v[212:213], 0, v[150:151]
	v_lshl_add_u64 v[152:153], v[212:213], 0, v[152:153]
	global_load_dwordx4 v[188:191], v[148:149], off offset:16 nt
	global_load_dwordx4 v[192:195], v[148:149], off nt
	global_load_dwordx4 v[180:183], v[148:149], off offset:528 nt
	global_load_dwordx4 v[184:187], v[148:149], off offset:512 nt
	global_load_dwordx4 v[172:175], v[150:151], off offset:16 nt
	global_load_dwordx4 v[176:179], v[150:151], off nt
	global_load_dwordx4 v[164:167], v[150:151], off offset:528 nt
	global_load_dwordx4 v[168:171], v[150:151], off offset:512 nt
	global_load_dwordx4 v[156:159], v[152:153], off offset:16 nt
	global_load_dwordx4 v[160:163], v[152:153], off nt
	s_nop 0
	global_load_dwordx4 v[148:151], v[152:153], off offset:528 nt
	s_nop 0
	global_load_dwordx4 v[152:155], v[152:153], off offset:512 nt
	v_readlane_b32 s38, v254, 52
	v_readlane_b32 s39, v254, 53
	v_readlane_b32 s70, v254, 18
	v_readlane_b32 s71, v254, 19
	v_readlane_b32 s72, v254, 20
	v_readlane_b32 s73, v254, 21
	v_readlane_b32 s74, v254, 22
	v_readlane_b32 s75, v254, 23
	v_readlane_b32 s76, v254, 24
	v_readlane_b32 s77, v254, 25
	v_readlane_b32 s78, v254, 26
	v_readlane_b32 s79, v254, 27
	v_readlane_b32 s80, v254, 28
	v_readlane_b32 s81, v254, 29
	v_readlane_b32 s82, v254, 30
	v_readlane_b32 s83, v254, 31
	s_waitcnt vmcnt(12)
	v_pk_fma_f32 v[248:249], v[10:11], v[142:143], v[234:235]
	v_pk_fma_f32 v[232:233], v[8:9], v[140:141], v[232:233]
	v_mul_f32_e32 v231, v249, v249
	v_cvt_pk_bf16_f32 v235, v248, v249
	v_pk_fma_f32 v[242:243], v[6:7], v[146:147], v[242:243]
	v_pk_fma_f32 v[240:241], v[4:5], v[144:145], v[240:241]
	v_mul_f32_e32 v252, v243, v243
	v_mul_f32_e32 v249, v241, v241
	v_mul_f32_e32 v1, v233, v233
	v_fmac_f32_e32 v249, v240, v240
	v_fmac_f32_e32 v252, v242, v242
	v_pk_fma_f32 v[236:237], v[36:37], v[136:137], v[236:237]
	v_cvt_pk_bf16_f32 v234, v232, v233
	v_fmac_f32_e32 v1, v232, v232
	v_cvt_pk_bf16_f32 v232, v240, v241
	v_add_f32_e32 v240, v249, v252
	v_pk_fma_f32 v[238:239], v[38:39], v[138:139], v[238:239]
	v_mul_f32_e32 v250, v237, v237
	v_fmac_f32_e32 v231, v248, v248
	v_add_f32_e32 v1, v240, v1
	v_pk_fma_f32 v[244:245], v[40:41], v[132:133], v[244:245]
	v_mul_f32_e32 v251, v239, v239
	v_fmac_f32_e32 v250, v236, v236
	v_add_f32_e32 v1, v231, v1
	v_pk_fma_f32 v[246:247], v[42:43], v[134:135], v[246:247]
	v_fmac_f32_e32 v251, v238, v238
	v_mul_f32_e32 v248, v245, v245
	v_add_f32_e32 v1, v250, v1
	v_mul_f32_e32 v253, v247, v247
	v_fmac_f32_e32 v248, v244, v244
	v_add_f32_e32 v1, v251, v1
	v_fmac_f32_e32 v253, v246, v246
	v_add_f32_e32 v1, v248, v1
	v_add_f32_e32 v1, v253, v1
	ds_bpermute_b32 v231, v226, v1
	v_lshlrev_b64 v[240:241], 11, v[210:211]
	v_lshl_add_u64 v[240:241], s[40:41], 0, v[240:241]
	v_cvt_pk_bf16_f32 v233, v242, v243
	v_lshl_add_u64 v[240:241], v[2:3], 1, v[240:241]
	s_waitcnt lgkmcnt(0)
	v_add_f32_e32 v1, v1, v231
	ds_bpermute_b32 v231, v227, v1
	global_store_dwordx4 v[240:241], v[232:235], off sc1
	s_nop 1
	v_cvt_pk_bf16_f32 v232, v236, v237
	v_cvt_pk_bf16_f32 v233, v238, v239
	v_cvt_pk_bf16_f32 v234, v244, v245
	v_cvt_pk_bf16_f32 v235, v246, v247
	global_store_dwordx4 v[240:241], v[232:235], off offset:256 sc1
	s_and_saveexec_b64 s[6:7], s[8:9]
	s_cbranch_execz .LBB0_671
	s_lshl_b32 s34, s66, 2
	v_lshlrev_b64 v[232:233], 6, v[210:211]
	s_ashr_i32 s35, s34, 31
	v_lshl_add_u64 v[232:233], s[18:19], 0, v[232:233]
	v_lshl_add_u64 v[232:233], s[34:35], 2, v[232:233]
	s_lshl_b32 s14, s42, 2
	s_waitcnt lgkmcnt(0)
	v_add_f32_e32 v1, v1, v231
	v_lshl_add_u64 v[232:233], v[232:233], 0, s[14:15]
	global_store_dword v[232:233], v1, off
.LBB0_671:
	s_or_b64 exec, exec, s[6:7]
	s_waitcnt vmcnt(8)
	v_pk_fma_f32 v[194:195], v[14:15], v[146:147], v[194:195]
	v_pk_fma_f32 v[192:193], v[12:13], v[144:145], v[192:193]
	v_pk_fma_f32 v[234:235], v[48:49], v[132:133], v[180:181]
	v_mul_f32_e32 v1, v193, v193
	v_mul_f32_e32 v180, v195, v195
	v_pk_fma_f32 v[188:189], v[16:17], v[140:141], v[188:189]
	v_fmac_f32_e32 v1, v192, v192
	v_fmac_f32_e32 v180, v194, v194
	v_add_f32_e32 v1, v1, v180
	v_mul_f32_e32 v180, v189, v189
	v_pk_fma_f32 v[190:191], v[18:19], v[142:143], v[190:191]
	v_fmac_f32_e32 v180, v188, v188
	v_add_f32_e32 v1, v1, v180
	v_mul_f32_e32 v180, v191, v191
	v_pk_fma_f32 v[184:185], v[44:45], v[136:137], v[184:185]
	v_fmac_f32_e32 v180, v190, v190
	v_add_f32_e32 v1, v180, v1
	v_mul_f32_e32 v180, v185, v185
	v_pk_fma_f32 v[186:187], v[46:47], v[138:139], v[186:187]
	v_fmac_f32_e32 v180, v184, v184
	v_add_f32_e32 v1, v180, v1
	v_mul_f32_e32 v180, v187, v187
	v_fmac_f32_e32 v180, v186, v186
	v_add_f32_e32 v1, v180, v1
	v_mul_f32_e32 v180, v235, v235
	v_pk_fma_f32 v[232:233], v[50:51], v[134:135], v[182:183]
	v_fmac_f32_e32 v180, v234, v234
	v_add_f32_e32 v1, v180, v1
	v_mul_f32_e32 v180, v233, v233
	v_fmac_f32_e32 v180, v232, v232
	v_add_f32_e32 v1, v180, v1
	v_cvt_pk_bf16_f32 v183, v190, v191
	ds_bpermute_b32 v190, v226, v1
	v_cvt_pk_bf16_f32 v182, v188, v189
	v_lshlrev_b64 v[188:189], 11, v[218:219]
	v_lshl_add_u64 v[188:189], s[40:41], 0, v[188:189]
	v_cvt_pk_bf16_f32 v180, v192, v193
	v_cvt_pk_bf16_f32 v181, v194, v195
	v_lshl_add_u64 v[188:189], v[2:3], 1, v[188:189]
	s_waitcnt lgkmcnt(0)
	v_add_f32_e32 v1, v1, v190
	global_store_dwordx4 v[188:189], v[180:183], off sc1
	ds_bpermute_b32 v180, v227, v1
	s_nop 0
	v_cvt_pk_bf16_f32 v182, v184, v185
	v_cvt_pk_bf16_f32 v183, v186, v187
	v_cvt_pk_bf16_f32 v184, v234, v235
	v_cvt_pk_bf16_f32 v185, v232, v233
	global_store_dwordx4 v[188:189], v[182:185], off offset:256 sc1
	s_and_saveexec_b64 s[6:7], s[8:9]
	s_cbranch_execz .LBB0_673
	s_waitcnt lgkmcnt(0)
	v_add_f32_e32 v1, v1, v180
	s_lshl_b32 s34, s66, 2
	v_lshlrev_b64 v[180:181], 6, v[218:219]
	s_ashr_i32 s35, s34, 31
	v_lshl_add_u64 v[180:181], s[18:19], 0, v[180:181]
	v_lshl_add_u64 v[180:181], s[34:35], 2, v[180:181]
	s_lshl_b32 s14, s42, 2
	v_lshl_add_u64 v[180:181], v[180:181], 0, s[14:15]
	global_store_dword v[180:181], v1, off
.LBB0_673:
	s_or_b64 exec, exec, s[6:7]
	s_waitcnt vmcnt(4)
	v_pk_fma_f32 v[178:179], v[22:23], v[146:147], v[178:179]
	v_pk_fma_f32 v[176:177], v[20:21], v[144:145], v[176:177]
	v_pk_fma_f32 v[182:183], v[56:57], v[132:133], v[164:165]
	v_mul_f32_e32 v1, v177, v177
	v_mul_f32_e32 v164, v179, v179
	v_pk_fma_f32 v[172:173], v[24:25], v[140:141], v[172:173]
	v_fmac_f32_e32 v1, v176, v176
	v_fmac_f32_e32 v164, v178, v178
	v_add_f32_e32 v1, v1, v164
	v_mul_f32_e32 v164, v173, v173
	v_pk_fma_f32 v[174:175], v[26:27], v[142:143], v[174:175]
	v_fmac_f32_e32 v164, v172, v172
	v_add_f32_e32 v1, v1, v164
	v_mul_f32_e32 v164, v175, v175
	v_pk_fma_f32 v[168:169], v[52:53], v[136:137], v[168:169]
	v_fmac_f32_e32 v164, v174, v174
	v_add_f32_e32 v1, v164, v1
	v_mul_f32_e32 v164, v169, v169
	v_pk_fma_f32 v[170:171], v[54:55], v[138:139], v[170:171]
	v_fmac_f32_e32 v164, v168, v168
	v_add_f32_e32 v1, v164, v1
	v_mul_f32_e32 v164, v171, v171
	v_fmac_f32_e32 v164, v170, v170
	v_add_f32_e32 v1, v164, v1
	v_mul_f32_e32 v164, v183, v183
	s_waitcnt lgkmcnt(0)
	v_pk_fma_f32 v[180:181], v[58:59], v[134:135], v[166:167]
	v_fmac_f32_e32 v164, v182, v182
	v_add_f32_e32 v1, v164, v1
	v_mul_f32_e32 v164, v181, v181
	v_fmac_f32_e32 v164, v180, v180
	v_add_f32_e32 v1, v164, v1
	v_cvt_pk_bf16_f32 v167, v174, v175
	ds_bpermute_b32 v174, v226, v1
	v_cvt_pk_bf16_f32 v166, v172, v173
	v_lshlrev_b64 v[172:173], 11, v[216:217]
	v_lshl_add_u64 v[172:173], s[40:41], 0, v[172:173]
	v_cvt_pk_bf16_f32 v164, v176, v177
	v_cvt_pk_bf16_f32 v165, v178, v179
	v_lshl_add_u64 v[172:173], v[2:3], 1, v[172:173]
	s_waitcnt lgkmcnt(0)
	v_add_f32_e32 v1, v1, v174
	global_store_dwordx4 v[172:173], v[164:167], off sc1
	ds_bpermute_b32 v164, v227, v1
	s_nop 0
	v_cvt_pk_bf16_f32 v166, v168, v169
	v_cvt_pk_bf16_f32 v167, v170, v171
	v_cvt_pk_bf16_f32 v168, v182, v183
	v_cvt_pk_bf16_f32 v169, v180, v181
	global_store_dwordx4 v[172:173], v[166:169], off offset:256 sc1
	s_and_saveexec_b64 s[6:7], s[8:9]
	s_cbranch_execz .LBB0_675
	s_waitcnt lgkmcnt(0)
	v_add_f32_e32 v1, v1, v164
	s_lshl_b32 s34, s66, 2
	v_lshlrev_b64 v[164:165], 6, v[216:217]
	s_ashr_i32 s35, s34, 31
	v_lshl_add_u64 v[164:165], s[18:19], 0, v[164:165]
	v_lshl_add_u64 v[164:165], s[34:35], 2, v[164:165]
	s_lshl_b32 s14, s42, 2
	v_lshl_add_u64 v[164:165], v[164:165], 0, s[14:15]
	global_store_dword v[164:165], v1, off
.LBB0_675:
	s_or_b64 exec, exec, s[6:7]
	s_waitcnt vmcnt(0)
	v_pk_fma_f32 v[162:163], v[30:31], v[146:147], v[162:163]
	v_pk_fma_f32 v[160:161], v[28:29], v[144:145], v[160:161]
	v_pk_fma_f32 v[166:167], v[64:65], v[132:133], v[148:149]
	v_mul_f32_e32 v1, v161, v161
	v_mul_f32_e32 v148, v163, v163
	v_pk_fma_f32 v[156:157], v[32:33], v[140:141], v[156:157]
	v_fmac_f32_e32 v1, v160, v160
	v_fmac_f32_e32 v148, v162, v162
	v_add_f32_e32 v1, v1, v148
	v_mul_f32_e32 v148, v157, v157
	v_pk_fma_f32 v[158:159], v[34:35], v[142:143], v[158:159]
	v_fmac_f32_e32 v148, v156, v156
	v_add_f32_e32 v1, v1, v148
	v_mul_f32_e32 v148, v159, v159
	v_pk_fma_f32 v[152:153], v[60:61], v[136:137], v[152:153]
	v_fmac_f32_e32 v148, v158, v158
	v_add_f32_e32 v1, v148, v1
	v_mul_f32_e32 v148, v153, v153
	v_pk_fma_f32 v[154:155], v[62:63], v[138:139], v[154:155]
	v_fmac_f32_e32 v148, v152, v152
	v_add_f32_e32 v1, v148, v1
	v_mul_f32_e32 v148, v155, v155
	v_fmac_f32_e32 v148, v154, v154
	v_add_f32_e32 v1, v148, v1
	v_mul_f32_e32 v148, v167, v167
	s_waitcnt lgkmcnt(0)
	v_pk_fma_f32 v[164:165], v[66:67], v[134:135], v[150:151]
	v_fmac_f32_e32 v148, v166, v166
	v_add_f32_e32 v1, v148, v1
	v_mul_f32_e32 v148, v165, v165
	v_fmac_f32_e32 v148, v164, v164
	v_add_f32_e32 v1, v148, v1
	v_cvt_pk_bf16_f32 v151, v158, v159
	ds_bpermute_b32 v158, v226, v1
	v_cvt_pk_bf16_f32 v150, v156, v157
	v_lshlrev_b64 v[156:157], 11, v[214:215]
	v_lshl_add_u64 v[156:157], s[40:41], 0, v[156:157]
	v_cvt_pk_bf16_f32 v148, v160, v161
	v_cvt_pk_bf16_f32 v149, v162, v163
	v_lshl_add_u64 v[156:157], v[2:3], 1, v[156:157]
	s_waitcnt lgkmcnt(0)
	v_add_f32_e32 v1, v1, v158
	global_store_dwordx4 v[156:157], v[148:151], off sc1
	ds_bpermute_b32 v148, v227, v1
	s_nop 0
	v_cvt_pk_bf16_f32 v150, v152, v153
	v_cvt_pk_bf16_f32 v151, v154, v155
	v_cvt_pk_bf16_f32 v152, v166, v167
	v_cvt_pk_bf16_f32 v153, v164, v165
	global_store_dwordx4 v[156:157], v[150:153], off offset:256 sc1
	s_and_saveexec_b64 s[6:7], s[8:9]
	s_cbranch_execz .LBB0_677
	s_waitcnt lgkmcnt(0)
	v_add_f32_e32 v1, v1, v148
	s_lshl_b32 s34, s66, 2
	v_lshlrev_b64 v[148:149], 6, v[214:215]
	s_ashr_i32 s35, s34, 31
	v_lshl_add_u64 v[148:149], s[18:19], 0, v[148:149]
	v_lshl_add_u64 v[148:149], s[34:35], 2, v[148:149]
	s_lshl_b32 s14, s42, 2
	v_lshl_add_u64 v[148:149], v[148:149], 0, s[14:15]
	global_store_dword v[148:149], v1, off
